# phase-order alternation keyed on workgroup index bit 3 (half of every XCD streams while the other half computes) instead of bit 0 (whole XCDs)
# baseline (speedup 1.0000x reference)
; #define LAS __attribute__((address_space(3)))
; __device__ __forceinline__ int lane_now() { int l; asm volatile("v_mbcnt_lo_u32_b32 %0, -1, 0\n\tv_mbcnt_hi_u32_b32 %0, -1, %0" : "=v"(l)); return l; }
; #define PH(k, ...) do { if (ka->ph_lo <= (k) && (k) < ka->ph_hi) { MKCTX(); __VA_ARGS__; if ((k) == PROBE_DUP) { GSYNC(); __VA_ARGS__; } if ((k) + 1 < ka->ph_hi) GSYNC(); } } while (0)
; __device__ __forceinline__ void ph_attn2(Ctx& C) {
;     const int lane = lane_now(), wave = C.wave, tid = wave * 64 + lane, r31 = lane & 31, hh = lane >> 5;
;     const bf16* z = (const bf16*)(C.ws + WS_ZQKV); bf16* og = (bf16*)(C.ws + WS_OG); float* lse_o = (float*)(C.ws + WS_LSE);
;     LAS bf16* vt = (LAS bf16*)C.lds; LAS bf16* kim = (LAS bf16*)(C.lds + 64 * AT_VTS * 2);
;     for (int unit = C.bid; unit < 1536; unit += C.nb) {
;         const int g = unit >> 9, rem = unit & 511, h = rem & 7, tile64 = rem >> 3;
; template <bool COOP>
; __global__ void __launch_bounds__(NTHR, 2) mega(Args args) {
;     ...
;     PH(P_ATTPREP, ph_attn2(C); ph_rprep2(C));
;     PH(P_GLORA, ph_attn_combine(C); __syncthreads(); ph_glora(C));
.Latt_setup:
	s_nop 0
	v_writelane_b32 v231, s88, 3
	s_load_dwordx2 s[78:79], s[88:89], 0xd0
	s_nop 0
	v_writelane_b32 v231, s89, 4
	s_nop 0
	v_readlane_b32 s0, v231, 1
	v_readlane_b32 s1, v231, 2
	s_load_dword s0, s[0:1], 0xe0
	v_readlane_b32 s1, v231, 0
	s_cmpk_gt_i32 s1, 0x5ff
	v_mbcnt_lo_u32_b32 v0, -1, 0
	v_mbcnt_hi_u32_b32 v0, -1, v0
	s_cmp_lg_u32 s100, 0
	s_cbranch_scc1 .Latt_go
	s_bitcmp1_b32 s1, 3
	s_cbranch_scc0 .Latt_go
	s_mov_b32 s100, 1
	s_branch .LBB0_326

; #define LAS __attribute__((address_space(3)))
; __device__ __forceinline__ int lane_now() { int l; asm volatile("v_mbcnt_lo_u32_b32 %0, -1, 0\n\tv_mbcnt_hi_u32_b32 %0, -1, %0" : "=v"(l)); return l; }
; template <class Mk> __device__ __forceinline__ void conv_run(Ctx& C, int nitems, const Mk& mk, LAS float* scr) {
;     const int lane = lane_now(); int it = C.gw; if (it >= nitems) return;
;     TrItem cur = mk(it); f32x4 v[8]; tr_load(cur, v, lane);
; __device__ __forceinline__ void ph_g1b(Ctx& C) {
;     LAS float* scr = (LAS float*)(C.lds + C.wave * 16384);
;     conv_natural(C, C.ka->in[20], D, D, (bf16*)(C.ws + WS_WOUT), scr);
;     conv_wgu(C, scr);
;     conv_natural(C, C.ka->in[24], FF, D, (bf16*)(C.ws + WS_WD), scr);
.Lg1b_setup:
	v_readlane_b32 s0, v231, 1
	v_readlane_b32 s1, v231, 2
	s_load_dword s52, s[0:1], 0xe0
	v_readlane_b32 s0, v231, 0
	s_load_dwordx4 s[20:23], s[88:89], 0xc8
	s_lshl_b32 s0, s0, 3
	s_add_i32 s51, s92, s0
	s_lshl_b32 s0, s92, 14
	s_waitcnt lgkmcnt(0)
	s_lshl_b32 s50, s52, 3
	s_add_i32 s53, s0, 0
	s_cmpk_gt_i32 s51, 0x7ff
	v_mbcnt_lo_u32_b32 v46, -1, 0
	v_mbcnt_hi_u32_b32 v46, -1, v46
	s_cmp_lg_u32 s101, 0
	s_cbranch_scc1 .Lg1b_go
	v_readlane_b32 s0, v231, 0
	s_nop 0
	s_bitcmp1_b32 s0, 3
	s_cbranch_scc0 .Lg1b_go
	s_mov_b32 s101, 1
	s_branch .LBB0_1086
